# 8x4 loops: DMAs spaced 2 tail MFMAs apart (setup hoisted before first tail MFMA)
# baseline (speedup 1.0000x reference)
; #define LDB_(dst, ks) _Pragma("unroll") for (int n = 0; n < 4; ++n) dst[n] = *(const bf16x8*)(sB + b_off + n * 2048 + (ks) * 1024)
; #define LDA_(dst, ks, h) _Pragma("unroll") for (int m = 0; m < 4; ++m) dst[m] = *(const bf16x8*)(sA + a_off + ((h) * 4 + m) * 2048 + (ks) * 1024)
; #define MMA_(A, B, h) _Pragma("unroll") for (int m = 0; m < 4; ++m) _Pragma("unroll") for (int n = 0; n < 4; ++n) \
;       acc[(h) * 4 + m][n] = SWAP ? MFMA16(B[n], A[m], acc[(h) * 4 + m][n]) : MFMA16(A[m], B[n], acc[(h) * 4 + m][n])
; template <int MF, int NF, bool SWAP = true>
; DI void gemm_main(f32x4 (&acc)[MF][NF], const u16* __restrict__ Ab, int lda, const u16* __restrict__ Bb, int ldb,
;                   int K, char* shm) {
;     ...
;   for (int t = 0; t < nt; ++t) {
;     const int cur = RING3 ? cur3 : (t & 1);
;     if constexpr (RING3) {
;       if (t + 2 < nt) G_STAGE(nxt3, t + 2);
;     } else {
;       if (t + 1 < nt) G_STAGE(cur ^ 1, t + 1);
;     }
;     const char* sA = shm + cur * STAGE;
;     const char* sB = sA + TILE_A;
;     if constexpr (MF == 8 && NF == 4) {
;       bf16x8 B0[4], B1[4], A0[4], A1[4], A2[4], A3[4];
;     ...
;       LDB_(B0, 0); LDA_(A0, 0, 0);
;       LDA_(A1, 0, 1); MMA_(A0, B0, 0);
;       LDB_(B1, 1); LDA_(A2, 1, 0); MMA_(A1, B0, 1);
;       LDA_(A3, 1, 1); MMA_(A2, B1, 0);
;       MMA_(A3, B1, 1);
.LBB0_146:
	s_and_b32 s19, s17, 0x10000
	v_add_u32_e32 v137, s19, v132
	v_add_u32_e32 v178, v137, v131
	ds_read_b128 v[138:141], v178 offset:32768
	ds_read_b128 v[142:145], v178 offset:34816
	ds_read_b128 v[146:149], v178 offset:36864
	ds_read_b128 v[150:153], v178 offset:38912
	v_add_u32_e32 v137, v137, v129
	ds_read_b128 v[154:157], v137
	ds_read_b128 v[158:161], v137 offset:2048
	ds_read_b128 v[162:165], v137 offset:4096
	ds_read_b128 v[166:169], v137 offset:6144
	ds_read_b128 v[170:173], v137 offset:8192
	s_cmp_gt_u32 s13, 14
	s_cbranch_scc1 .Lg_rot146_last
	s_cmp_eq_u32 s13, 0
	s_cbranch_scc1 .Lg_rot146_first
	s_xor_b32 s20, s19, 0x10000
	v_add_u32_e32 v179, s20, v128
	s_nop 0
	v_readfirstlane_b32 s20, v179
	s_nop 1
	s_add_u32 m0, s20, 0x0
	v_mfma_f32_16x16x32_bf16 v[60:63], v[186:189], v[190:193], v[60:63]
	global_load_lds_dwordx4 v251, s[98:99]
	s_add_u32 m0, s20, 0x2000
	v_mfma_f32_16x16x32_bf16 v[56:59], v[194:197], v[190:193], v[56:59]
	v_mfma_f32_16x16x32_bf16 v[52:55], v[198:201], v[190:193], v[52:55]
	global_load_lds_dwordx4 v250, s[98:99]
	s_add_u32 m0, s20, 0x4000
	v_mfma_f32_16x16x32_bf16 v[48:51], v[212:215], v[190:193], v[48:51]
	v_mfma_f32_16x16x32_bf16 v[44:47], v[186:189], v[216:219], v[44:47]
	global_load_lds_dwordx4 v249, s[98:99]
	s_add_u32 m0, s20, 0x6000
	v_mfma_f32_16x16x32_bf16 v[40:43], v[194:197], v[216:219], v[40:43]
	v_mfma_f32_16x16x32_bf16 v[36:39], v[198:201], v[216:219], v[36:39]
	global_load_lds_dwordx4 v248, s[98:99]
	s_add_u32 m0, s20, 0x8000
	v_mfma_f32_16x16x32_bf16 v[32:35], v[212:215], v[216:219], v[32:35]
	v_mfma_f32_16x16x32_bf16 v[28:31], v[186:189], v[220:223], v[28:31]
	global_load_lds_dwordx4 v247, s[100:101]
	s_add_u32 m0, s20, 0xa000
	v_mfma_f32_16x16x32_bf16 v[24:27], v[194:197], v[220:223], v[24:27]
	v_mfma_f32_16x16x32_bf16 v[20:23], v[198:201], v[220:223], v[20:23]
	global_load_lds_dwordx4 v246, s[100:101]
	s_add_u32 m0, s20, 0xc000
	v_mfma_f32_16x16x32_bf16 v[16:19], v[212:215], v[220:223], v[16:19]
	v_mfma_f32_16x16x32_bf16 v[12:15], v[186:189], v[224:227], v[12:15]
	global_load_lds_dwordx4 v245, s[100:101]
	s_add_u32 m0, s20, 0xe000
	v_mfma_f32_16x16x32_bf16 v[8:11], v[194:197], v[224:227], v[8:11]
	v_mfma_f32_16x16x32_bf16 v[4:7], v[198:201], v[224:227], v[4:7]
	global_load_lds_dwordx4 v244, s[100:101]
	v_mfma_f32_16x16x32_bf16 v[0:3], v[212:215], v[224:227], v[0:3]
	s_add_u32 s98, s98, 0x80
	s_addc_u32 s99, s99, 0
	s_add_u32 s100, s100, 0x80
	s_addc_u32 s101, s101, 0
	s_branch .Lg_rot146_main

; #define LDB_(dst, ks) _Pragma("unroll") for (int n = 0; n < 4; ++n) dst[n] = *(const bf16x8*)(sB + b_off + n * 2048 + (ks) * 1024)
; #define LDA_(dst, ks, h) _Pragma("unroll") for (int m = 0; m < 4; ++m) dst[m] = *(const bf16x8*)(sA + a_off + ((h) * 4 + m) * 2048 + (ks) * 1024)
; #define MMA_(A, B, h) _Pragma("unroll") for (int m = 0; m < 4; ++m) _Pragma("unroll") for (int n = 0; n < 4; ++n) \
;       acc[(h) * 4 + m][n] = SWAP ? MFMA16(B[n], A[m], acc[(h) * 4 + m][n]) : MFMA16(A[m], B[n], acc[(h) * 4 + m][n])
; template <int MF, int NF, bool SWAP = true>
; DI void gemm_main(f32x4 (&acc)[MF][NF], const u16* __restrict__ Ab, int lda, const u16* __restrict__ Bb, int ldb,
;                   int K, char* shm) {
;     ...
;   for (int t = 0; t < nt; ++t) {
;     const int cur = RING3 ? cur3 : (t & 1);
;     if constexpr (RING3) {
;       if (t + 2 < nt) G_STAGE(nxt3, t + 2);
;     } else {
;       if (t + 1 < nt) G_STAGE(cur ^ 1, t + 1);
;     }
;     const char* sA = shm + cur * STAGE;
;     const char* sB = sA + TILE_A;
;     if constexpr (MF == 8 && NF == 4) {
;       bf16x8 B0[4], B1[4], A0[4], A1[4], A2[4], A3[4];
;     ...
;       LDB_(B0, 0); LDA_(A0, 0, 0);
;       LDA_(A1, 0, 1); MMA_(A0, B0, 0);
;       LDB_(B1, 1); LDA_(A2, 1, 0); MMA_(A1, B0, 1);
;       LDA_(A3, 1, 1); MMA_(A2, B1, 0);
;       MMA_(A3, B1, 1);
.LBB0_244:
	s_and_b32 s18, s15, 0x10000
	v_add_u32_e32 v154, s18, v136
	v_add_u32_e32 v178, v154, v132
	ds_read_b128 v[138:141], v178 offset:32768
	ds_read_b128 v[142:145], v178 offset:34816
	ds_read_b128 v[146:149], v178 offset:36864
	ds_read_b128 v[150:153], v178 offset:38912
	v_add_u32_e32 v186, v154, v129
	ds_read_b128 v[154:157], v186
	ds_read_b128 v[158:161], v186 offset:2048
	ds_read_b128 v[162:165], v186 offset:4096
	ds_read_b128 v[166:169], v186 offset:6144
	ds_read_b128 v[170:173], v186 offset:8192
	s_cmp_gt_u32 s17, 14
	s_cbranch_scc1 .Lg_rot244_last
	s_cmp_eq_u32 s17, 0
	s_cbranch_scc1 .Lg_rot244_first
	s_xor_b32 s19, s18, 0x10000
	v_add_u32_e32 v179, s19, v128
	s_nop 0
	v_readfirstlane_b32 s19, v179
	s_nop 1
	s_add_u32 m0, s19, 0x0
	v_mfma_f32_16x16x32_bf16 v[60:63], v[188:191], v[192:195], v[60:63]
	global_load_lds_dwordx4 v251, s[98:99]
	s_add_u32 m0, s19, 0x2000
	v_mfma_f32_16x16x32_bf16 v[56:59], v[196:199], v[192:195], v[56:59]
	v_mfma_f32_16x16x32_bf16 v[52:55], v[212:215], v[192:195], v[52:55]
	global_load_lds_dwordx4 v250, s[98:99]
	s_add_u32 m0, s19, 0x4000
	v_mfma_f32_16x16x32_bf16 v[48:51], v[216:219], v[192:195], v[48:51]
	v_mfma_f32_16x16x32_bf16 v[44:47], v[188:191], v[220:223], v[44:47]
	global_load_lds_dwordx4 v249, s[98:99]
	s_add_u32 m0, s19, 0x6000
	v_mfma_f32_16x16x32_bf16 v[40:43], v[196:199], v[220:223], v[40:43]
	v_mfma_f32_16x16x32_bf16 v[36:39], v[212:215], v[220:223], v[36:39]
	global_load_lds_dwordx4 v248, s[98:99]
	s_add_u32 m0, s19, 0x8000
	v_mfma_f32_16x16x32_bf16 v[32:35], v[216:219], v[220:223], v[32:35]
	v_mfma_f32_16x16x32_bf16 v[28:31], v[188:191], v[224:227], v[28:31]
	global_load_lds_dwordx4 v247, s[100:101]
	s_add_u32 m0, s19, 0xa000
	v_mfma_f32_16x16x32_bf16 v[24:27], v[196:199], v[224:227], v[24:27]
	v_mfma_f32_16x16x32_bf16 v[20:23], v[212:215], v[224:227], v[20:23]
	global_load_lds_dwordx4 v246, s[100:101]
	s_add_u32 m0, s19, 0xc000
	v_mfma_f32_16x16x32_bf16 v[16:19], v[216:219], v[224:227], v[16:19]
	v_mfma_f32_16x16x32_bf16 v[12:15], v[188:191], v[228:231], v[12:15]
	global_load_lds_dwordx4 v245, s[100:101]
	s_add_u32 m0, s19, 0xe000
	v_mfma_f32_16x16x32_bf16 v[8:11], v[196:199], v[228:231], v[8:11]
	v_mfma_f32_16x16x32_bf16 v[4:7], v[212:215], v[228:231], v[4:7]
	global_load_lds_dwordx4 v244, s[100:101]
	v_mfma_f32_16x16x32_bf16 v[0:3], v[216:219], v[228:231], v[0:3]
	s_add_u32 s98, s98, 0x80
	s_addc_u32 s99, s99, 0
	s_add_u32 s100, s100, 0x80
	s_addc_u32 s101, s101, 0
	s_branch .Lg_rot244_main

; #define LDB_(dst, ks) _Pragma("unroll") for (int n = 0; n < 4; ++n) dst[n] = *(const bf16x8*)(sB + b_off + n * 2048 + (ks) * 1024)
; #define LDA_(dst, ks, h) _Pragma("unroll") for (int m = 0; m < 4; ++m) dst[m] = *(const bf16x8*)(sA + a_off + ((h) * 4 + m) * 2048 + (ks) * 1024)
; #define MMA_(A, B, h) _Pragma("unroll") for (int m = 0; m < 4; ++m) _Pragma("unroll") for (int n = 0; n < 4; ++n) \
;       acc[(h) * 4 + m][n] = SWAP ? MFMA16(B[n], A[m], acc[(h) * 4 + m][n]) : MFMA16(A[m], B[n], acc[(h) * 4 + m][n])
; template <int MF, int NF, bool SWAP = true>
; DI void gemm_main(f32x4 (&acc)[MF][NF], const u16* __restrict__ Ab, int lda, const u16* __restrict__ Bb, int ldb,
;                   int K, char* shm) {
;     ...
;   for (int t = 0; t < nt; ++t) {
;     const int cur = RING3 ? cur3 : (t & 1);
;     if constexpr (RING3) {
;       if (t + 2 < nt) G_STAGE(nxt3, t + 2);
;     } else {
;       if (t + 1 < nt) G_STAGE(cur ^ 1, t + 1);
;     }
;     const char* sA = shm + cur * STAGE;
;     const char* sB = sA + TILE_A;
;     if constexpr (MF == 8 && NF == 4) {
;       bf16x8 B0[4], B1[4], A0[4], A1[4], A2[4], A3[4];
;     ...
;       LDB_(B0, 0); LDA_(A0, 0, 0);
;       LDA_(A1, 0, 1); MMA_(A0, B0, 0);
;       LDB_(B1, 1); LDA_(A2, 1, 0); MMA_(A1, B0, 1);
;       LDA_(A3, 1, 1); MMA_(A2, B1, 0);
;       MMA_(A3, B1, 1);
.LBB0_314:
	s_and_b32 s16, s5, 0x10000
	v_add_u32_e32 v138, s16, v136
	v_add_u32_e32 v186, v138, v129
	v_add_u32_e32 v178, v138, v132
	ds_read_b128 v[138:141], v186
	ds_read_b128 v[158:161], v186 offset:2048
	ds_read_b128 v[142:145], v178 offset:32768
	ds_read_b128 v[146:149], v178 offset:34816
	ds_read_b128 v[150:153], v178 offset:36864
	ds_read_b128 v[154:157], v178 offset:38912
	ds_read_b128 v[162:165], v186 offset:4096
	ds_read_b128 v[166:169], v186 offset:6144
	ds_read_b128 v[170:173], v186 offset:8192
	s_cmp_gt_u32 s15, 14
	s_cbranch_scc1 .Lg_rot314_last
	s_cmp_eq_u32 s15, 0
	s_cbranch_scc1 .Lg_rot314_first
	s_xor_b32 s17, s16, 0x10000
	v_add_u32_e32 v179, s17, v128
	s_nop 0
	v_readfirstlane_b32 s17, v179
	s_nop 1
	s_add_u32 m0, s17, 0x0
	v_mfma_f32_16x16x32_bf16 v[60:63], v[188:191], v[192:195], v[60:63]
	global_load_lds_dwordx4 v251, s[98:99]
	s_add_u32 m0, s17, 0x2000
	v_mfma_f32_16x16x32_bf16 v[56:59], v[188:191], v[196:199], v[56:59]
	v_mfma_f32_16x16x32_bf16 v[52:55], v[188:191], v[212:215], v[52:55]
	global_load_lds_dwordx4 v250, s[98:99]
	s_add_u32 m0, s17, 0x4000
	v_mfma_f32_16x16x32_bf16 v[48:51], v[188:191], v[216:219], v[48:51]
	v_mfma_f32_16x16x32_bf16 v[44:47], v[220:223], v[192:195], v[44:47]
	global_load_lds_dwordx4 v249, s[98:99]
	s_add_u32 m0, s17, 0x6000
	v_mfma_f32_16x16x32_bf16 v[40:43], v[220:223], v[196:199], v[40:43]
	v_mfma_f32_16x16x32_bf16 v[36:39], v[220:223], v[212:215], v[36:39]
	global_load_lds_dwordx4 v248, s[98:99]
	s_add_u32 m0, s17, 0x8000
	v_mfma_f32_16x16x32_bf16 v[32:35], v[220:223], v[216:219], v[32:35]
	v_mfma_f32_16x16x32_bf16 v[28:31], v[224:227], v[192:195], v[28:31]
	global_load_lds_dwordx4 v247, s[100:101]
	s_add_u32 m0, s17, 0xa000
	v_mfma_f32_16x16x32_bf16 v[24:27], v[224:227], v[196:199], v[24:27]
	v_mfma_f32_16x16x32_bf16 v[20:23], v[224:227], v[212:215], v[20:23]
	global_load_lds_dwordx4 v246, s[100:101]
	s_add_u32 m0, s17, 0xc000
	v_mfma_f32_16x16x32_bf16 v[16:19], v[224:227], v[216:219], v[16:19]
	v_mfma_f32_16x16x32_bf16 v[12:15], v[228:231], v[192:195], v[12:15]
	global_load_lds_dwordx4 v245, s[100:101]
	s_add_u32 m0, s17, 0xe000
	v_mfma_f32_16x16x32_bf16 v[4:7], v[228:231], v[196:199], v[4:7]
	v_mfma_f32_16x16x32_bf16 v[0:3], v[228:231], v[212:215], v[0:3]
	global_load_lds_dwordx4 v244, s[100:101]
	v_mfma_f32_16x16x32_bf16 v[8:11], v[228:231], v[216:219], v[8:11]
	s_add_u32 s98, s98, 0x80
	s_addc_u32 s99, s99, 0
	s_add_u32 s100, s100, 0x80
	s_addc_u32 s101, s101, 0
	s_branch .Lg_rot314_main

; #define LDB_(dst, ks) _Pragma("unroll") for (int n = 0; n < 4; ++n) dst[n] = *(const bf16x8*)(sB + b_off + n * 2048 + (ks) * 1024)
; #define LDA_(dst, ks, h) _Pragma("unroll") for (int m = 0; m < 4; ++m) dst[m] = *(const bf16x8*)(sA + a_off + ((h) * 4 + m) * 2048 + (ks) * 1024)
; #define MMA_(A, B, h) _Pragma("unroll") for (int m = 0; m < 4; ++m) _Pragma("unroll") for (int n = 0; n < 4; ++n) \
;       acc[(h) * 4 + m][n] = SWAP ? MFMA16(B[n], A[m], acc[(h) * 4 + m][n]) : MFMA16(A[m], B[n], acc[(h) * 4 + m][n])
; template <int MF, int NF, bool SWAP = true>
; DI void gemm_main(f32x4 (&acc)[MF][NF], const u16* __restrict__ Ab, int lda, const u16* __restrict__ Bb, int ldb,
;                   int K, char* shm) {
;     ...
;   for (int t = 0; t < nt; ++t) {
;     const int cur = RING3 ? cur3 : (t & 1);
;     if constexpr (RING3) {
;       if (t + 2 < nt) G_STAGE(nxt3, t + 2);
;     } else {
;       if (t + 1 < nt) G_STAGE(cur ^ 1, t + 1);
;     }
;     const char* sA = shm + cur * STAGE;
;     const char* sB = sA + TILE_A;
;     if constexpr (MF == 8 && NF == 4) {
;       bf16x8 B0[4], B1[4], A0[4], A1[4], A2[4], A3[4];
;     ...
;       LDB_(B0, 0); LDA_(A0, 0, 0);
;       LDA_(A1, 0, 1); MMA_(A0, B0, 0);
;       LDB_(B1, 1); LDA_(A2, 1, 0); MMA_(A1, B0, 1);
;       LDA_(A3, 1, 1); MMA_(A2, B1, 0);
;       MMA_(A3, B1, 1);
.LBB0_553:
	s_and_b32 s21, s18, 0x10000
	v_add_u32_e32 v162, s21, v143
	v_add_u32_e32 v186, v162, v142
	ds_read_b128 v[146:149], v186 offset:32768
	ds_read_b128 v[150:153], v186 offset:34816
	ds_read_b128 v[154:157], v186 offset:36864
	ds_read_b128 v[158:161], v186 offset:38912
	v_add_u32_e32 v194, v162, v141
	ds_read_b128 v[162:165], v194
	ds_read_b128 v[166:169], v194 offset:2048
	ds_read_b128 v[170:173], v194 offset:4096
	ds_read_b128 v[174:177], v194 offset:6144
	ds_read_b128 v[178:181], v194 offset:8192
	s_cmp_gt_u32 s20, 2
	s_cbranch_scc1 .Lg_rot553_last
	s_cmp_eq_u32 s20, 0
	s_cbranch_scc1 .Lg_rot553_first
	s_xor_b32 s22, s21, 0x10000
	v_add_u32_e32 v195, s22, v132
	s_nop 0
	v_readfirstlane_b32 s22, v195
	s_nop 1
	s_add_u32 m0, s22, 0x0
	v_mfma_f32_16x16x32_bf16 v[60:63], v[196:199], v[212:215], v[60:63]
	global_load_lds_dwordx4 v251, s[98:99]
	s_add_u32 m0, s22, 0x2000
	v_mfma_f32_16x16x32_bf16 v[56:59], v[216:219], v[212:215], v[56:59]
	v_mfma_f32_16x16x32_bf16 v[52:55], v[220:223], v[212:215], v[52:55]
	global_load_lds_dwordx4 v250, s[98:99]
	s_add_u32 m0, s22, 0x4000
	v_mfma_f32_16x16x32_bf16 v[48:51], v[224:227], v[212:215], v[48:51]
	v_mfma_f32_16x16x32_bf16 v[44:47], v[196:199], v[228:231], v[44:47]
	global_load_lds_dwordx4 v249, s[98:99]
	s_add_u32 m0, s22, 0x6000
	v_mfma_f32_16x16x32_bf16 v[40:43], v[216:219], v[228:231], v[40:43]
	v_mfma_f32_16x16x32_bf16 v[36:39], v[220:223], v[228:231], v[36:39]
	global_load_lds_dwordx4 v248, s[98:99]
	s_add_u32 m0, s22, 0x8000
	v_mfma_f32_16x16x32_bf16 v[32:35], v[224:227], v[228:231], v[32:35]
	v_mfma_f32_16x16x32_bf16 v[28:31], v[196:199], v[232:235], v[28:31]
	global_load_lds_dwordx4 v247, s[100:101]
	s_add_u32 m0, s22, 0xa000
	v_mfma_f32_16x16x32_bf16 v[24:27], v[216:219], v[232:235], v[24:27]
	v_mfma_f32_16x16x32_bf16 v[20:23], v[220:223], v[232:235], v[20:23]
	global_load_lds_dwordx4 v246, s[100:101]
	s_add_u32 m0, s22, 0xc000
	v_mfma_f32_16x16x32_bf16 v[16:19], v[224:227], v[232:235], v[16:19]
	v_mfma_f32_16x16x32_bf16 v[12:15], v[196:199], v[236:239], v[12:15]
	global_load_lds_dwordx4 v245, s[100:101]
	s_add_u32 m0, s22, 0xe000
	v_mfma_f32_16x16x32_bf16 v[4:7], v[216:219], v[236:239], v[4:7]
	v_mfma_f32_16x16x32_bf16 v[0:3], v[220:223], v[236:239], v[0:3]
	global_load_lds_dwordx4 v244, s[100:101]
	v_mfma_f32_16x16x32_bf16 v[8:11], v[224:227], v[236:239], v[8:11]
	s_add_u32 s98, s98, 0x80
	s_addc_u32 s99, s99, 0
	s_add_u32 s100, s100, 0x80
	s_addc_u32 s101, s101, 0
	s_branch .Lg_rot553_main

; #define LDB_(dst, ks) _Pragma("unroll") for (int n = 0; n < 4; ++n) dst[n] = *(const bf16x8*)(sB + b_off + n * 2048 + (ks) * 1024)
; #define LDA_(dst, ks, h) _Pragma("unroll") for (int m = 0; m < 4; ++m) dst[m] = *(const bf16x8*)(sA + a_off + ((h) * 4 + m) * 2048 + (ks) * 1024)
; #define MMA_(A, B, h) _Pragma("unroll") for (int m = 0; m < 4; ++m) _Pragma("unroll") for (int n = 0; n < 4; ++n) \
;       acc[(h) * 4 + m][n] = SWAP ? MFMA16(B[n], A[m], acc[(h) * 4 + m][n]) : MFMA16(A[m], B[n], acc[(h) * 4 + m][n])
; template <int MF, int NF, bool SWAP = true>
; DI void gemm_main(f32x4 (&acc)[MF][NF], const u16* __restrict__ Ab, int lda, const u16* __restrict__ Bb, int ldb,
;                   int K, char* shm) {
;     ...
;   for (int t = 0; t < nt; ++t) {
;     const int cur = RING3 ? cur3 : (t & 1);
;     if constexpr (RING3) {
;       if (t + 2 < nt) G_STAGE(nxt3, t + 2);
;     } else {
;       if (t + 1 < nt) G_STAGE(cur ^ 1, t + 1);
;     }
;     const char* sA = shm + cur * STAGE;
;     const char* sB = sA + TILE_A;
;     if constexpr (MF == 8 && NF == 4) {
;       bf16x8 B0[4], B1[4], A0[4], A1[4], A2[4], A3[4];
;     ...
;       LDB_(B0, 0); LDA_(A0, 0, 0);
;       LDA_(A1, 0, 1); MMA_(A0, B0, 0);
;       LDB_(B1, 1); LDA_(A2, 1, 0); MMA_(A1, B0, 1);
;       LDA_(A3, 1, 1); MMA_(A2, B1, 0);
;       MMA_(A3, B1, 1);
.LBB0_589:
	s_and_b32 s21, s16, 0x10000
	v_add_u32_e32 v137, s21, v132
	v_add_u32_e32 v178, v137, v131
	ds_read_b128 v[138:141], v178 offset:32768
	ds_read_b128 v[142:145], v178 offset:34816
	ds_read_b128 v[146:149], v178 offset:36864
	ds_read_b128 v[150:153], v178 offset:38912
	v_add_u32_e32 v137, v137, v129
	ds_read_b128 v[154:157], v137
	ds_read_b128 v[158:161], v137 offset:2048
	ds_read_b128 v[162:165], v137 offset:4096
	ds_read_b128 v[166:169], v137 offset:6144
	ds_read_b128 v[170:173], v137 offset:8192
	s_cmp_gt_u32 s15, 14
	s_cbranch_scc1 .Lg_rot589_last
	s_cmp_eq_u32 s15, 0
	s_cbranch_scc1 .Lg_rot589_first
	s_xor_b32 s22, s21, 0x10000
	v_add_u32_e32 v179, s22, v128
	s_nop 0
	v_readfirstlane_b32 s22, v179
	s_nop 1
	s_add_u32 m0, s22, 0x0
	v_mfma_f32_16x16x32_bf16 v[60:63], v[186:189], v[190:193], v[60:63]
	global_load_lds_dwordx4 v251, s[98:99]
	s_add_u32 m0, s22, 0x2000
	v_mfma_f32_16x16x32_bf16 v[56:59], v[194:197], v[190:193], v[56:59]
	v_mfma_f32_16x16x32_bf16 v[52:55], v[198:201], v[190:193], v[52:55]
	global_load_lds_dwordx4 v250, s[98:99]
	s_add_u32 m0, s22, 0x4000
	v_mfma_f32_16x16x32_bf16 v[48:51], v[218:221], v[190:193], v[48:51]
	v_mfma_f32_16x16x32_bf16 v[44:47], v[186:189], v[222:225], v[44:47]
	global_load_lds_dwordx4 v249, s[98:99]
	s_add_u32 m0, s22, 0x6000
	v_mfma_f32_16x16x32_bf16 v[40:43], v[194:197], v[222:225], v[40:43]
	v_mfma_f32_16x16x32_bf16 v[36:39], v[198:201], v[222:225], v[36:39]
	global_load_lds_dwordx4 v248, s[98:99]
	s_add_u32 m0, s22, 0x8000
	v_mfma_f32_16x16x32_bf16 v[32:35], v[218:221], v[222:225], v[32:35]
	v_mfma_f32_16x16x32_bf16 v[28:31], v[186:189], v[226:229], v[28:31]
	global_load_lds_dwordx4 v247, s[100:101]
	s_add_u32 m0, s22, 0xa000
	v_mfma_f32_16x16x32_bf16 v[24:27], v[194:197], v[226:229], v[24:27]
	v_mfma_f32_16x16x32_bf16 v[20:23], v[198:201], v[226:229], v[20:23]
	global_load_lds_dwordx4 v246, s[100:101]
	s_add_u32 m0, s22, 0xc000
	v_mfma_f32_16x16x32_bf16 v[16:19], v[218:221], v[226:229], v[16:19]
	v_mfma_f32_16x16x32_bf16 v[12:15], v[186:189], v[230:233], v[12:15]
	global_load_lds_dwordx4 v245, s[100:101]
	s_add_u32 m0, s22, 0xe000
	v_mfma_f32_16x16x32_bf16 v[8:11], v[194:197], v[230:233], v[8:11]
	v_mfma_f32_16x16x32_bf16 v[4:7], v[198:201], v[230:233], v[4:7]
	global_load_lds_dwordx4 v244, s[100:101]
	v_mfma_f32_16x16x32_bf16 v[0:3], v[218:221], v[230:233], v[0:3]
	s_add_u32 s98, s98, 0x80
	s_addc_u32 s99, s99, 0
	s_add_u32 s100, s100, 0x80
	s_addc_u32 s101, s101, 0
	s_branch .Lg_rot589_main

; #define LDB_(dst, ks) _Pragma("unroll") for (int n = 0; n < 4; ++n) dst[n] = *(const bf16x8*)(sB + b_off + n * 2048 + (ks) * 1024)
; #define LDA_(dst, ks, h) _Pragma("unroll") for (int m = 0; m < 4; ++m) dst[m] = *(const bf16x8*)(sA + a_off + ((h) * 4 + m) * 2048 + (ks) * 1024)
; #define MMA_(A, B, h) _Pragma("unroll") for (int m = 0; m < 4; ++m) _Pragma("unroll") for (int n = 0; n < 4; ++n) \
;       acc[(h) * 4 + m][n] = SWAP ? MFMA16(B[n], A[m], acc[(h) * 4 + m][n]) : MFMA16(A[m], B[n], acc[(h) * 4 + m][n])
; template <int MF, int NF, bool SWAP = true>
; DI void gemm_main(f32x4 (&acc)[MF][NF], const u16* __restrict__ Ab, int lda, const u16* __restrict__ Bb, int ldb,
;                   int K, char* shm) {
;     ...
;   for (int t = 0; t < nt; ++t) {
;     const int cur = RING3 ? cur3 : (t & 1);
;     if constexpr (RING3) {
;       if (t + 2 < nt) G_STAGE(nxt3, t + 2);
;     } else {
;       if (t + 1 < nt) G_STAGE(cur ^ 1, t + 1);
;     }
;     const char* sA = shm + cur * STAGE;
;     const char* sB = sA + TILE_A;
;     if constexpr (MF == 8 && NF == 4) {
;       bf16x8 B0[4], B1[4], A0[4], A1[4], A2[4], A3[4];
;     ...
;       LDB_(B0, 0); LDA_(A0, 0, 0);
;       LDA_(A1, 0, 1); MMA_(A0, B0, 0);
;       LDB_(B1, 1); LDA_(A2, 1, 0); MMA_(A1, B0, 1);
;       LDA_(A3, 1, 1); MMA_(A2, B1, 0);
;       MMA_(A3, B1, 1);
.LBB0_819:
	s_and_b32 s19, s17, 0x10000
	v_add_u32_e32 v137, s19, v132
	v_add_u32_e32 v178, v137, v131
	ds_read_b128 v[138:141], v178 offset:32768
	ds_read_b128 v[142:145], v178 offset:34816
	ds_read_b128 v[146:149], v178 offset:36864
	ds_read_b128 v[150:153], v178 offset:38912
	v_add_u32_e32 v137, v137, v130
	ds_read_b128 v[154:157], v137
	ds_read_b128 v[158:161], v137 offset:2048
	ds_read_b128 v[162:165], v137 offset:4096
	ds_read_b128 v[166:169], v137 offset:6144
	ds_read_b128 v[170:173], v137 offset:8192
	s_cmp_gt_u32 s18, 2
	s_cbranch_scc1 .Lg_rot819_last
	s_cmp_eq_u32 s18, 0
	s_cbranch_scc1 .Lg_rot819_first
	s_xor_b32 s20, s19, 0x10000
	v_add_u32_e32 v179, s20, v129
	s_nop 0
	v_readfirstlane_b32 s20, v179
	s_nop 1
	s_add_u32 m0, s20, 0x0
	v_mfma_f32_16x16x32_bf16 v[60:63], v[186:189], v[190:193], v[60:63]
	global_load_lds_dwordx4 v251, s[98:99]
	s_add_u32 m0, s20, 0x2000
	v_mfma_f32_16x16x32_bf16 v[56:59], v[194:197], v[190:193], v[56:59]
	v_mfma_f32_16x16x32_bf16 v[52:55], v[198:201], v[190:193], v[52:55]
	global_load_lds_dwordx4 v250, s[98:99]
	s_add_u32 m0, s20, 0x4000
	v_mfma_f32_16x16x32_bf16 v[48:51], v[218:221], v[190:193], v[48:51]
	v_mfma_f32_16x16x32_bf16 v[44:47], v[186:189], v[222:225], v[44:47]
	global_load_lds_dwordx4 v249, s[98:99]
	s_add_u32 m0, s20, 0x6000
	v_mfma_f32_16x16x32_bf16 v[40:43], v[194:197], v[222:225], v[40:43]
	v_mfma_f32_16x16x32_bf16 v[36:39], v[198:201], v[222:225], v[36:39]
	global_load_lds_dwordx4 v248, s[98:99]
	s_add_u32 m0, s20, 0x8000
	v_mfma_f32_16x16x32_bf16 v[32:35], v[218:221], v[222:225], v[32:35]
	v_mfma_f32_16x16x32_bf16 v[28:31], v[186:189], v[226:229], v[28:31]
	global_load_lds_dwordx4 v247, s[100:101]
	s_add_u32 m0, s20, 0xa000
	v_mfma_f32_16x16x32_bf16 v[24:27], v[194:197], v[226:229], v[24:27]
	v_mfma_f32_16x16x32_bf16 v[20:23], v[198:201], v[226:229], v[20:23]
	global_load_lds_dwordx4 v246, s[100:101]
	s_add_u32 m0, s20, 0xc000
	v_mfma_f32_16x16x32_bf16 v[16:19], v[218:221], v[226:229], v[16:19]
	v_mfma_f32_16x16x32_bf16 v[8:11], v[186:189], v[230:233], v[8:11]
	global_load_lds_dwordx4 v245, s[100:101]
	s_add_u32 m0, s20, 0xe000
	v_mfma_f32_16x16x32_bf16 v[4:7], v[194:197], v[230:233], v[4:7]
	v_mfma_f32_16x16x32_bf16 v[0:3], v[198:201], v[230:233], v[0:3]
	global_load_lds_dwordx4 v244, s[100:101]
	v_mfma_f32_16x16x32_bf16 v[12:15], v[218:221], v[230:233], v[12:15]
	s_add_u32 s98, s98, 0x80
	s_addc_u32 s99, s99, 0
	s_add_u32 s100, s100, 0x80
	s_addc_u32 s101, s101, 0
	s_branch .Lg_rot819_main
